# WKV scan: prep waves (coefficient preparation / y store) run at s_setprio 2; tests whether the per-chunk barrier waits on the prep waves
# baseline (speedup 1.0000x reference)
.LBB0_547:
	s_and_b32 s93, s92, 1
	s_mov_b64 s[4:5], -1
	s_and_b64 vcc, exec, s[42:43]
	s_cbranch_vccz .LBB0_641
	s_setprio 2
	s_waitcnt vmcnt(0)
	v_mov_b64_e32 v[94:95], v[108:109]
	v_mov_b64_e32 v[96:97], v[110:111]
	v_mov_b64_e32 v[98:99], v[112:113]
	v_mov_b64_e32 v[100:101], v[114:115]
	v_mov_b64_e32 v[102:103], v[116:117]
	s_cmpk_gt_u32 s92, 0xfd
	s_cbranch_scc1 .Lscan_noload
	s_mov_b64 s[4:5], 0x4000
	v_lshl_add_u64 v[104:105], v[104:105], 0, s[4:5]
	v_lshlrev_b64 v[24:25], 1, v[104:105]
	v_lshl_add_u64 v[26:27], s[24:25], 0, v[24:25]
	v_lshl_add_u64 v[28:29], s[26:27], 0, v[24:25]
	v_lshl_add_u64 v[30:31], s[28:29], 0, v[24:25]
	v_lshl_add_u64 v[32:33], s[30:31], 0, v[24:25]
	global_load_dwordx2 v[108:109], v[26:27], off
	global_load_dwordx2 v[110:111], v[28:29], off
	global_load_dwordx2 v[112:113], v[30:31], off
	global_load_dwordx2 v[114:115], v[32:33], off
	v_lshl_add_u64 v[24:25], s[34:35], 0, v[24:25]
	global_load_dwordx2 v[116:117], v[24:25], off

.LBB0_735:
	s_setprio 0
	s_waitcnt lgkmcnt(0)
	s_cmp_lt_i32 s2, 7
	s_cselect_b64 s[4:5], -1, 0
	s_cmp_gt_i32 s3, 7
	s_cselect_b64 s[6:7], -1, 0
	s_and_b64 s[4:5], s[4:5], s[6:7]
	s_andn2_b64 vcc, exec, s[4:5]
	s_cbranch_vccnz .LBB0_766
	v_readlane_b32 s2, v254, 0
	s_waitcnt vmcnt(0) lgkmcnt(0)
	s_lshl_b32 s2, s2, 6
	s_sub_i32 s2, 0, s2
	s_waitcnt vmcnt(0)
	s_barrier
	v_mbcnt_lo_u32_b32 v0, -1, 0
	v_mbcnt_hi_u32_b32 v0, -1, v0
	s_nop 0
	v_cmp_eq_u32_e32 vcc, s2, v0
	s_and_saveexec_b64 s[78:79], vcc
	s_cbranch_execz .LBB0_765
	s_add_i32 s2, 0, 0x20040
	v_mov_b32_e32 v0, s2
	ds_read_b32 v1, v0
	s_add_i32 s2, 0, 0x20044
	v_mov_b32_e32 v0, s2
	ds_read_b32 v0, v0
	s_waitcnt lgkmcnt(1)
	v_cmp_ne_u32_e32 vcc, 0, v1
	s_cbranch_vccnz .LBB0_743
	s_cmp_eq_u32 s97, 0
	s_cselect_b64 s[2:3], -1, 0
	s_cmp_eq_u32 s97, 1
	s_cselect_b64 s[4:5], -1, 0
	s_cmp_eq_u32 s97, 2
	s_cselect_b64 s[6:7], -1, 0
	s_cmp_eq_u32 s97, 3
	s_cselect_b64 s[8:9], -1, 0
	s_cmp_eq_u32 s97, 4
	s_cselect_b64 s[10:11], -1, 0
	s_cmp_eq_u32 s97, 5
	s_cselect_b64 s[12:13], -1, 0
	s_cmp_eq_u32 s97, 6
	s_cselect_b64 s[14:15], -1, 0
	s_cmp_eq_u32 s97, 7
	s_cselect_b64 s[16:17], -1, 0
	s_cmp_eq_u32 s97, 8
	s_cselect_b64 s[18:19], -1, 0
	s_cmp_eq_u32 s97, 9
	s_cselect_b64 s[20:21], -1, 0
	s_cmp_eq_u32 s97, 10
	s_cselect_b64 s[22:23], -1, 0
	s_cmp_eq_u32 s97, 11
	s_cselect_b64 s[24:25], -1, 0
	s_add_u32 s80, s70, 0x1000
	s_addc_u32 s81, s71, 0
	s_cmp_eq_u32 s97, 12
	s_cselect_b64 s[26:27], -1, 0
	s_add_u32 s82, s70, 0x1100
	s_addc_u32 s83, s71, 0
	s_cmp_eq_u32 s97, 13
	s_cselect_b64 s[28:29], -1, 0
	s_add_u32 s84, s70, 0x1200
	s_addc_u32 s85, s71, 0
	s_cmp_eq_u32 s97, 14
	s_cselect_b64 s[30:31], -1, 0
	s_add_u32 s86, s70, 0x1300
	s_addc_u32 s87, s71, 0
	s_cmp_eq_u32 s97, 15
	s_cselect_b64 s[34:35], -1, 0
	v_mov_b32_e32 v2, 0
	v_mov_b32_e32 v1, 0
	s_branch .LBB0_740
